# v101 + grid barrier: L1 invalidate (buffer_inv sc1) issued right behind the arrive atomic instead of after the release
# speedup vs baseline: 1.0253x; 1.0116x over previous
; __device__ __forceinline__ unsigned xb_ld(unsigned* p)              { return __hip_atomic_load(p, __ATOMIC_RELAXED, __HIP_MEMORY_SCOPE_AGENT); }
; __device__ __forceinline__ unsigned xb_add(unsigned* p, unsigned v) { return __hip_atomic_fetch_add(p, v, __ATOMIC_RELAXED, __HIP_MEMORY_SCOPE_AGENT); }
; #define XB_SPIN(cond, bar) do { unsigned _sp = 0; while (cond) { __builtin_amdgcn_s_sleep(1); \
;     if ((++_sp & 255u) == 0u) { if (xb_ld(&(bar)[XB_TMO])) break; if (_sp > XB_SPIN_CAP) { atomicAdd(&(bar)[XB_TMO], 1u); break; } } } } while (0)
; __device__ __forceinline__ void xcd_barrier(const XcdBarrier& b) {
;     ...
;         const unsigned old = xb_add(&bar[XB_XSUB(b.x)], 1u);
;         const unsigned gen = old / nloc;
;         if (old + 1u == (gen + 1u) * nloc) {
;             __builtin_amdgcn_fence(__ATOMIC_RELEASE, "agent");
;             asm volatile("s_waitcnt vmcnt(0)" ::: "memory");
;             const unsigned og = xb_add(&bar[XB_TOP], 1u);
;             const unsigned tg = og / nx;
;             if (og + 1u == (tg + 1u) * nx) xb_add(&bar[XB_TOPGEN], 1u);
;             else XB_SPIN(xb_ld(&bar[XB_TOPGEN]) == tg, bar);
;             __builtin_amdgcn_fence(__ATOMIC_ACQUIRE, "agent");
;             xb_add(&bar[XB_XGEN(b.x)], 1u);
;             asm volatile("s_waitcnt vmcnt(0)" ::: "memory");
;         } else {
;             XB_SPIN(xb_ld(&bar[XB_XGEN(b.x)]) == gen, bar);
;             __builtin_amdgcn_fence(__ATOMIC_ACQUIRE, "agent");
;             asm volatile("s_waitcnt vmcnt(0)" ::: "memory");
.LBB0_811:
	v_readlane_b32 s2, v252, 3
	v_readlane_b32 s3, v252, 4
	v_cvt_f32_u32_e32 v0, v3
	v_sub_u32_e32 v5, 0, v3
	v_rcp_iflag_f32_e32 v0, v0
	s_nop 1
	global_atomic_add v4, v1, v240, s[2:3] sc0
	buffer_inv sc1
	v_mul_f32_e32 v0, 0x4f7ffffe, v0
	v_cvt_u32_f32_e32 v0, v0
	v_mul_lo_u32 v5, v5, v0
	v_mul_hi_u32 v5, v0, v5
	v_add_u32_e32 v0, v0, v5
	s_waitcnt vmcnt(0)
	v_mul_hi_u32 v0, v4, v0
	v_mul_lo_u32 v5, v0, v3
	v_sub_u32_e32 v5, v4, v5
	v_add_u32_e32 v6, 1, v0
	v_cmp_ge_u32_e32 vcc, v5, v3
	v_add_u32_e32 v4, 1, v4
	s_nop 0
	v_cndmask_b32_e32 v0, v0, v6, vcc
	v_sub_u32_e32 v6, v5, v3
	v_cndmask_b32_e32 v5, v5, v6, vcc
	v_add_u32_e32 v6, 1, v0
	v_cmp_ge_u32_e32 vcc, v5, v3
	s_nop 1
	v_cndmask_b32_e32 v0, v0, v6, vcc
	v_mul_lo_u32 v5, v3, v0
	v_add_u32_e32 v3, v5, v3
	v_cmp_ne_u32_e32 vcc, v4, v3
	s_and_saveexec_b64 s[2:3], vcc
	s_xor_b64 s[2:3], exec, s[2:3]
	s_cbranch_execz .LBB0_825
	v_readlane_b32 s4, v252, 5
	v_readlane_b32 s5, v252, 6
	s_waitcnt lgkmcnt(0)
	s_nop 3
	global_load_dword v2, v1, s[4:5] sc1
	s_waitcnt vmcnt(0)
	v_cmp_eq_u32_e32 vcc, v2, v0
	s_and_saveexec_b64 s[4:5], vcc
	s_cbranch_execz .LBB0_824
	s_mov_b32 s18, 1
	s_mov_b64 s[8:9], 0
	s_branch .LBB0_815

; __device__ __forceinline__ unsigned xb_ld(unsigned* p)              { return __hip_atomic_load(p, __ATOMIC_RELAXED, __HIP_MEMORY_SCOPE_AGENT); }
; #define XB_SPIN(cond, bar) do { unsigned _sp = 0; while (cond) { __builtin_amdgcn_s_sleep(1); \
;     if ((++_sp & 255u) == 0u) { if (xb_ld(&(bar)[XB_TMO])) break; if (_sp > XB_SPIN_CAP) { atomicAdd(&(bar)[XB_TMO], 1u); break; } } } } while (0)
; __device__ __forceinline__ void xcd_barrier(const XcdBarrier& b) {
;     ...
;             XB_SPIN(xb_ld(&bar[XB_XGEN(b.x)]) == gen, bar);
;             __builtin_amdgcn_fence(__ATOMIC_ACQUIRE, "agent");
;             asm volatile("s_waitcnt vmcnt(0)" ::: "memory");
.LBB0_824:
	s_or_b64 exec, exec, s[4:5]
	s_waitcnt vmcnt(0)
	s_nop 0
	s_waitcnt vmcnt(0)
